# v55: P0 row sum-of-squares wave reduction via DPP row ops + permlane swaps instead of six ds_bpermute round trips (bit-identical pairing)
# baseline (speedup 1.0000x reference)
; __device__ __forceinline__ unsigned cvtpk(float lo, float hi) { f32x2_t v = {lo, hi}; bf16x2_t b = __builtin_convertvector(v, bf16x2_t); return __builtin_bit_cast(unsigned, b); }
; __device__ __forceinline__ float wave_sum(float v) {
; #pragma unroll
;     for (int o = 1; o < 64; o <<= 1) v += __shfl_xor(v, o);
;     return v;
; }
; __global__ void __launch_bounds__(NTHREADS, 2) fwd_kernel(Params P) {
;     ...
;                 float sq[2];
; #pragma unroll
;                 for (int q = 0; q < 2; ++q) { float s2 = 0.f;
; #pragma unroll
;                     for (int j = 0; j < 4; ++j) s2 += (v[q][j][0] * v[q][j][0] + v[q][j][1] * v[q][j][1]) + (v[q][j][2] * v[q][j][2] + v[q][j][3] * v[q][j][3]);
;                     sq[q] = wave_sum(s2); }
; #pragma unroll
;                 for (int q = 0; q < 2; ++q) { const int m = m0 + q; u32x2* o8 = (u32x2*)(XA + (size_t)m * D) + lane;
; #pragma unroll
;                     for (int j = 0; j < 4; ++j) o8[64 * j] = (u32x2){cvtpk(v[q][j][0], v[q][j][1]), cvtpk(v[q][j][2], v[q][j][3])};
;                     if (lane == 0) ssq0[(size_t)m * 16] = __builtin_amdgcn_rsqf(sq[q] * (1.0f / D) + EPS); }
.LBB0_256:
	s_waitcnt vmcnt(7)
	v_mul_f32_e32 v68, v3, v3
	v_mul_f32_e32 v69, v5, v5
	v_fmac_f32_e32 v68, v2, v2
	v_fmac_f32_e32 v69, v4, v4
	v_add_f32_e32 v68, v68, v69
	s_waitcnt vmcnt(6)
	v_mul_f32_e32 v69, v7, v7
	v_mul_f32_e32 v79, v9, v9
	v_fmac_f32_e32 v69, v6, v6
	v_fmac_f32_e32 v79, v8, v8
	v_add_f32_e32 v69, v69, v79
	v_add_f32_e32 v68, v68, v69
	s_waitcnt vmcnt(5)
	v_mul_f32_e32 v69, v11, v11
	v_mul_f32_e32 v79, v13, v13
	v_fmac_f32_e32 v69, v10, v10
	v_fmac_f32_e32 v79, v12, v12
	v_add_f32_e32 v69, v69, v79
	v_add_f32_e32 v68, v68, v69
	s_waitcnt vmcnt(4)
	v_mul_f32_e32 v69, v15, v15
	v_mul_f32_e32 v79, v17, v17
	v_fmac_f32_e32 v69, v14, v14
	v_fmac_f32_e32 v79, v16, v16
	v_add_f32_e32 v69, v69, v79
	s_waitcnt vmcnt(3)
	v_mul_f32_e32 v79, v19, v19
	s_waitcnt lgkmcnt(0)
	v_mul_f32_e32 v80, v21, v21
	v_fmac_f32_e32 v79, v18, v18
	v_fmac_f32_e32 v80, v20, v20
	v_add_f32_e32 v79, v79, v80
	s_waitcnt vmcnt(2)
	v_mul_f32_e32 v80, v23, v23
	v_mul_f32_e32 v81, v25, v25
	v_fmac_f32_e32 v80, v22, v22
	v_fmac_f32_e32 v81, v24, v24
	v_add_f32_e32 v80, v80, v81
	v_add_f32_e32 v79, v79, v80
	s_waitcnt vmcnt(1)
	v_mul_f32_e32 v80, v27, v27
	v_mul_f32_e32 v81, v29, v29
	v_fmac_f32_e32 v80, v26, v26
	v_fmac_f32_e32 v81, v28, v28
	v_add_f32_e32 v80, v80, v81
	v_add_f32_e32 v79, v79, v80
	s_waitcnt vmcnt(0)
	v_mul_f32_e32 v80, v31, v31
	v_mul_f32_e32 v81, v33, v33
	v_fmac_f32_e32 v80, v30, v30
	v_fmac_f32_e32 v81, v32, v32
	v_add_f32_e32 v80, v80, v81
	v_add_f32_e32 v68, v68, v69
	v_add_f32_e32 v79, v79, v80
	s_nop 1
	v_add_f32_dpp v68, v68, v68 quad_perm:[1,0,3,2] row_mask:0xf bank_mask:0xf
	v_add_f32_dpp v79, v79, v79 quad_perm:[1,0,3,2] row_mask:0xf bank_mask:0xf
	v_cvt_pk_bf16_f32 v84, v2, v3
	v_cvt_pk_bf16_f32 v85, v4, v5
	v_add_f32_dpp v68, v68, v68 quad_perm:[2,3,0,1] row_mask:0xf bank_mask:0xf
	v_add_f32_dpp v79, v79, v79 quad_perm:[2,3,0,1] row_mask:0xf bank_mask:0xf
	s_nop 1
	v_add_f32_dpp v68, v68, v68 row_half_mirror row_mask:0xf bank_mask:0xf
	v_add_f32_dpp v79, v79, v79 row_half_mirror row_mask:0xf bank_mask:0xf
	s_nop 1
	v_add_f32_dpp v68, v68, v68 row_ror:8 row_mask:0xf bank_mask:0xf
	v_add_f32_dpp v79, v79, v79 row_ror:8 row_mask:0xf bank_mask:0xf
	v_mov_b32_e32 v69, v68
	v_mov_b32_e32 v80, v79
	s_nop 1
	v_permlane16_swap_b32_e32 v68, v69
	v_permlane16_swap_b32_e32 v79, v80
	v_add_f32_e32 v81, v68, v69
	v_add_f32_e32 v79, v79, v80
	v_lshl_add_u64 v[68:69], s[68:69], 0, v[66:67]
	v_mov_b32_e32 v82, v81
	v_mov_b32_e32 v80, v79
	s_nop 1
	v_permlane32_swap_b32_e32 v81, v82
	v_permlane32_swap_b32_e32 v79, v80
	v_add_co_u32_e32 v86, vcc, s24, v68
	s_nop 1
	v_addc_co_u32_e32 v87, vcc, 0, v69, vcc
	global_store_dwordx2 v[86:87], v[84:85], off
	v_cvt_pk_bf16_f32 v84, v6, v7
	v_cvt_pk_bf16_f32 v85, v8, v9
	global_store_dwordx2 v[86:87], v[84:85], off offset:512
	v_cvt_pk_bf16_f32 v84, v10, v11
	v_cvt_pk_bf16_f32 v85, v12, v13
	global_store_dwordx2 v[86:87], v[84:85], off offset:1024
	v_cvt_pk_bf16_f32 v84, v14, v15
	v_cvt_pk_bf16_f32 v85, v16, v17
	global_store_dwordx2 v[86:87], v[84:85], off offset:1536
	s_and_saveexec_b64 s[72:73], s[0:1]
	s_cbranch_execz .LBB0_258
	s_waitcnt lgkmcnt(1)
	v_add_f32_e32 v81, v81, v82
	v_fmamk_f32 v81, v81, 0x3a800000, v77
	v_rsq_f32_e32 v81, v81
	s_add_u32 s74, s68, s20
	s_addc_u32 s75, s69, s21
	global_store_dword v78, v81, s[74:75]
